# f12 + P5 SwiGLU epilogue with packed f32 ops, reciprocal of (1+e)/rs^2 folded, fewer VALU instructions
# speedup vs baseline: 1.0066x; 1.0066x over previous
; __device__ __forceinline__ unsigned pk2(float lo, float hi) { f32x2 v = {lo, hi}; bf16x2_t b = __builtin_convertvector(v, bf16x2_t); return __builtin_bit_cast(unsigned, b); }
; __device__ __forceinline__ float sigmoidf_(float x) { return frcp(1.0f + fexp(-x)); }
;     __device__ __forceinline__ void operator()(const Acc& acc, const Unit& u, int wr, int wc, int fr, int fq) const {
;         const int row0 = u.pm * BM + wr * 64 + fr; const int col0 = u.pn * HALF + wc * 32 + 8 * fq;
;         float rsv[2][4];
; #pragma unroll
;         for (int ai = 0; ai < 2; ++ai)
; #pragma unroll
;             for (int m = 0; m < 4; ++m) rsv[ai][m] = RTAB[u.sub * BM + ai * HALF + wr * 64 + m * 16 + fr];
; #pragma unroll
;         for (int ai = 0; ai < 2; ++ai)
; #pragma unroll
;             for (int m = 0; m < 4; ++m) { const int row = row0 + ai * HALF + m * 16; const float rs = rsv[ai][m];
;                 float o[8];
; #pragma unroll
;                 for (int n = 0; n < 2; ++n)
; #pragma unroll
;                     for (int e = 0; e < 4; ++e) { const float g = acc[ai][0][m][n][e] * rs, up = acc[ai][1][m][n][e] * rs; o[4 * n + e] = g * sigmoidf_(g) * up; }
;                 u32x4 w; w.x = pk2(o[0], o[1]); w.y = pk2(o[2], o[3]); w.z = pk2(o[4], o[5]); w.w = pk2(o[6], o[7]);
;                 *(u32x4*)(ACT + (size_t)row * DFF + col0) = w; }
;     }
.LBB0_1107:
	v_lshl_add_u32 v146, s49, 10, v154
	ds_read2_b32 v[180:181], v146 offset1:16
	ds_read2_b32 v[182:183], v146 offset0:32 offset1:48
	ds_read2_b32 v[184:185], v146 offset0:128 offset1:144
	ds_read2_b32 v[186:187], v146 offset0:160 offset1:176
	v_lshl_or_b32 v178, s50, 7, v155
	s_lshl_b32 s28, s26, 8
	v_lshlrev_b32_e32 v178, 1, v178
	s_mul_i32 s28, s28, s46
	v_mad_u32_u24 v172, v152, s46, v178
	s_add_u32 s28, s8, s28
	s_addc_u32 s29, s9, 0
	s_waitcnt lgkmcnt(0)
	v_mul_f32_e32 v174, 0xbfb8aa3b, v180
	v_mul_f32_e32 v176, v180, v180
	v_rcp_f32_e32 v176, v176
	s_nop 0
	v_pk_mul_f32 v[160:161], v[126:127], v[174:175] op_sel_hi:[1,0]
	v_pk_mul_f32 v[118:119], v[126:127], v[118:119]
	v_exp_f32_e32 v160, v160
	v_exp_f32_e32 v161, v161
	v_pk_mul_f32 v[162:163], v[128:129], v[174:175] op_sel_hi:[1,0]
	v_pk_mul_f32 v[120:121], v[128:129], v[120:121]
	v_exp_f32_e32 v162, v162
	v_exp_f32_e32 v163, v163
	v_pk_fma_f32 v[160:161], v[160:161], v[176:177], v[176:177] op_sel_hi:[1,0,0]
	v_rcp_f32_e32 v160, v160
	v_rcp_f32_e32 v161, v161
	v_pk_mul_f32 v[164:165], v[122:123], v[174:175] op_sel_hi:[1,0]
	v_pk_mul_f32 v[114:115], v[122:123], v[114:115]
	v_exp_f32_e32 v164, v164
	v_exp_f32_e32 v165, v165
	v_mul_f32_e32 v190, 0xbfb8aa3b, v181
	v_mul_f32_e32 v192, v181, v181
	v_rcp_f32_e32 v192, v192
	v_pk_fma_f32 v[162:163], v[162:163], v[176:177], v[176:177] op_sel_hi:[1,0,0]
	v_rcp_f32_e32 v162, v162
	v_rcp_f32_e32 v163, v163
	v_pk_mul_f32 v[118:119], v[118:119], v[160:161]
	v_cvt_pk_bf16_f32 v168, v118, v119
	v_pk_mul_f32 v[166:167], v[124:125], v[174:175] op_sel_hi:[1,0]
	v_pk_mul_f32 v[116:117], v[124:125], v[116:117]
	v_exp_f32_e32 v166, v166
	v_exp_f32_e32 v167, v167
	v_pk_fma_f32 v[164:165], v[164:165], v[176:177], v[176:177] op_sel_hi:[1,0,0]
	v_rcp_f32_e32 v164, v164
	v_rcp_f32_e32 v165, v165
	v_pk_mul_f32 v[120:121], v[120:121], v[162:163]
	v_cvt_pk_bf16_f32 v169, v120, v121
	v_pk_mul_f32 v[160:161], v[110:111], v[190:191] op_sel_hi:[1,0]
	v_pk_mul_f32 v[102:103], v[110:111], v[102:103]
	v_exp_f32_e32 v160, v160
	v_exp_f32_e32 v161, v161
	v_pk_fma_f32 v[166:167], v[166:167], v[176:177], v[176:177] op_sel_hi:[1,0,0]
	v_rcp_f32_e32 v166, v166
	v_rcp_f32_e32 v167, v167
	v_pk_mul_f32 v[114:115], v[114:115], v[164:165]
	v_cvt_pk_bf16_f32 v170, v114, v115
	v_pk_mul_f32 v[162:163], v[112:113], v[190:191] op_sel_hi:[1,0]
	v_pk_mul_f32 v[104:105], v[112:113], v[104:105]
	v_exp_f32_e32 v162, v162
	v_exp_f32_e32 v163, v163
	v_pk_fma_f32 v[160:161], v[160:161], v[192:193], v[192:193] op_sel_hi:[1,0,0]
	v_rcp_f32_e32 v160, v160
	v_rcp_f32_e32 v161, v161
	v_pk_mul_f32 v[116:117], v[116:117], v[166:167]
	v_cvt_pk_bf16_f32 v171, v116, v117
	global_store_dwordx4 v172, v[168:171], s[28:29]
	s_add_u32 s28, s28, 0x2c000
	s_addc_u32 s29, s29, 0
	v_pk_mul_f32 v[164:165], v[106:107], v[190:191] op_sel_hi:[1,0]
	v_pk_mul_f32 v[98:99], v[106:107], v[98:99]
	v_exp_f32_e32 v164, v164
	v_exp_f32_e32 v165, v165
	v_mul_f32_e32 v174, 0xbfb8aa3b, v182
	v_mul_f32_e32 v176, v182, v182
	v_rcp_f32_e32 v176, v176
	v_pk_fma_f32 v[162:163], v[162:163], v[192:193], v[192:193] op_sel_hi:[1,0,0]
	v_rcp_f32_e32 v162, v162
	v_rcp_f32_e32 v163, v163
	v_pk_mul_f32 v[102:103], v[102:103], v[160:161]
	v_cvt_pk_bf16_f32 v168, v102, v103
	v_pk_mul_f32 v[166:167], v[108:109], v[190:191] op_sel_hi:[1,0]
	v_pk_mul_f32 v[100:101], v[108:109], v[100:101]
	v_exp_f32_e32 v166, v166
	v_exp_f32_e32 v167, v167
	v_pk_fma_f32 v[164:165], v[164:165], v[192:193], v[192:193] op_sel_hi:[1,0,0]
	v_rcp_f32_e32 v164, v164
	v_rcp_f32_e32 v165, v165
	v_pk_mul_f32 v[104:105], v[104:105], v[162:163]
	v_cvt_pk_bf16_f32 v169, v104, v105
	v_pk_mul_f32 v[160:161], v[94:95], v[174:175] op_sel_hi:[1,0]
	v_pk_mul_f32 v[86:87], v[94:95], v[86:87]
	v_exp_f32_e32 v160, v160
	v_exp_f32_e32 v161, v161
	v_pk_fma_f32 v[166:167], v[166:167], v[192:193], v[192:193] op_sel_hi:[1,0,0]
	v_rcp_f32_e32 v166, v166
	v_rcp_f32_e32 v167, v167
	v_pk_mul_f32 v[98:99], v[98:99], v[164:165]
	v_cvt_pk_bf16_f32 v170, v98, v99
	v_pk_mul_f32 v[162:163], v[96:97], v[174:175] op_sel_hi:[1,0]
	v_pk_mul_f32 v[88:89], v[96:97], v[88:89]
	v_exp_f32_e32 v162, v162
	v_exp_f32_e32 v163, v163
	v_pk_fma_f32 v[160:161], v[160:161], v[176:177], v[176:177] op_sel_hi:[1,0,0]
	v_rcp_f32_e32 v160, v160
	v_rcp_f32_e32 v161, v161
	v_pk_mul_f32 v[100:101], v[100:101], v[166:167]
	v_cvt_pk_bf16_f32 v171, v100, v101
	global_store_dwordx4 v172, v[168:171], s[28:29]
	s_add_u32 s28, s28, 0x2c000
	s_addc_u32 s29, s29, 0
	v_pk_mul_f32 v[164:165], v[90:91], v[174:175] op_sel_hi:[1,0]
	v_pk_mul_f32 v[82:83], v[90:91], v[82:83]
	v_exp_f32_e32 v164, v164
	v_exp_f32_e32 v165, v165
	v_mul_f32_e32 v190, 0xbfb8aa3b, v183
	v_mul_f32_e32 v192, v183, v183
	v_rcp_f32_e32 v192, v192
	v_pk_fma_f32 v[162:163], v[162:163], v[176:177], v[176:177] op_sel_hi:[1,0,0]
	v_rcp_f32_e32 v162, v162
	v_rcp_f32_e32 v163, v163
	v_pk_mul_f32 v[86:87], v[86:87], v[160:161]
	v_cvt_pk_bf16_f32 v168, v86, v87
	v_pk_mul_f32 v[166:167], v[92:93], v[174:175] op_sel_hi:[1,0]
	v_pk_mul_f32 v[84:85], v[92:93], v[84:85]
	v_exp_f32_e32 v166, v166
	v_exp_f32_e32 v167, v167
	v_pk_fma_f32 v[164:165], v[164:165], v[176:177], v[176:177] op_sel_hi:[1,0,0]
	v_rcp_f32_e32 v164, v164
	v_rcp_f32_e32 v165, v165
	v_pk_mul_f32 v[88:89], v[88:89], v[162:163]
	v_cvt_pk_bf16_f32 v169, v88, v89
	v_pk_mul_f32 v[160:161], v[78:79], v[190:191] op_sel_hi:[1,0]
	v_pk_mul_f32 v[70:71], v[78:79], v[70:71]
	v_exp_f32_e32 v160, v160
	v_exp_f32_e32 v161, v161
	v_pk_fma_f32 v[166:167], v[166:167], v[176:177], v[176:177] op_sel_hi:[1,0,0]
	v_rcp_f32_e32 v166, v166
	v_rcp_f32_e32 v167, v167
	v_pk_mul_f32 v[82:83], v[82:83], v[164:165]
; __device__ __forceinline__ unsigned pk2(float lo, float hi) { f32x2 v = {lo, hi}; bf16x2_t b = __builtin_convertvector(v, bf16x2_t); return __builtin_bit_cast(unsigned, b); }
; __device__ __forceinline__ float sigmoidf_(float x) { return frcp(1.0f + fexp(-x)); }
;     __device__ __forceinline__ void operator()(const Acc& acc, const Unit& u, int wr, int wc, int fr, int fq) const {
;         const int row0 = u.pm * BM + wr * 64 + fr; const int col0 = u.pn * HALF + wc * 32 + 8 * fq;
;         float rsv[2][4];
; #pragma unroll
;         for (int ai = 0; ai < 2; ++ai)
; #pragma unroll
;             for (int m = 0; m < 4; ++m) rsv[ai][m] = RTAB[u.sub * BM + ai * HALF + wr * 64 + m * 16 + fr];
; #pragma unroll
;         for (int ai = 0; ai < 2; ++ai)
; #pragma unroll
;             for (int m = 0; m < 4; ++m) { const int row = row0 + ai * HALF + m * 16; const float rs = rsv[ai][m];
;                 float o[8];
; #pragma unroll
;                 for (int n = 0; n < 2; ++n)
; #pragma unroll
;                     for (int e = 0; e < 4; ++e) { const float g = acc[ai][0][m][n][e] * rs, up = acc[ai][1][m][n][e] * rs; o[4 * n + e] = g * sigmoidf_(g) * up; }
;                 u32x4 w; w.x = pk2(o[0], o[1]); w.y = pk2(o[2], o[3]); w.z = pk2(o[4], o[5]); w.w = pk2(o[6], o[7]);
;                 *(u32x4*)(ACT + (size_t)row * DFF + col0) = w; }
;     }
	v_cvt_pk_bf16_f32 v170, v82, v83
	v_pk_mul_f32 v[162:163], v[80:81], v[190:191] op_sel_hi:[1,0]
	v_pk_mul_f32 v[72:73], v[80:81], v[72:73]
	v_exp_f32_e32 v162, v162
	v_exp_f32_e32 v163, v163
	v_pk_fma_f32 v[160:161], v[160:161], v[192:193], v[192:193] op_sel_hi:[1,0,0]
	v_rcp_f32_e32 v160, v160
	v_rcp_f32_e32 v161, v161
	v_pk_mul_f32 v[84:85], v[84:85], v[166:167]
	v_cvt_pk_bf16_f32 v171, v84, v85
	global_store_dwordx4 v172, v[168:171], s[28:29]
	s_add_u32 s28, s28, 0x2c000
	s_addc_u32 s29, s29, 0
	v_pk_mul_f32 v[164:165], v[74:75], v[190:191] op_sel_hi:[1,0]
	v_pk_mul_f32 v[66:67], v[74:75], v[66:67]
	v_exp_f32_e32 v164, v164
	v_exp_f32_e32 v165, v165
	v_mul_f32_e32 v174, 0xbfb8aa3b, v184
	v_mul_f32_e32 v176, v184, v184
	v_rcp_f32_e32 v176, v176
	v_pk_fma_f32 v[162:163], v[162:163], v[192:193], v[192:193] op_sel_hi:[1,0,0]
	v_rcp_f32_e32 v162, v162
	v_rcp_f32_e32 v163, v163
	v_pk_mul_f32 v[70:71], v[70:71], v[160:161]
	v_cvt_pk_bf16_f32 v168, v70, v71
	v_pk_mul_f32 v[166:167], v[76:77], v[190:191] op_sel_hi:[1,0]
	v_pk_mul_f32 v[68:69], v[76:77], v[68:69]
	v_exp_f32_e32 v166, v166
	v_exp_f32_e32 v167, v167
	v_pk_fma_f32 v[164:165], v[164:165], v[192:193], v[192:193] op_sel_hi:[1,0,0]
	v_rcp_f32_e32 v164, v164
	v_rcp_f32_e32 v165, v165
	v_pk_mul_f32 v[72:73], v[72:73], v[162:163]
	v_cvt_pk_bf16_f32 v169, v72, v73
	v_pk_mul_f32 v[160:161], v[62:63], v[174:175] op_sel_hi:[1,0]
	v_pk_mul_f32 v[54:55], v[62:63], v[54:55]
	v_exp_f32_e32 v160, v160
	v_exp_f32_e32 v161, v161
	v_pk_fma_f32 v[166:167], v[166:167], v[192:193], v[192:193] op_sel_hi:[1,0,0]
	v_rcp_f32_e32 v166, v166
	v_rcp_f32_e32 v167, v167
	v_pk_mul_f32 v[66:67], v[66:67], v[164:165]
	v_cvt_pk_bf16_f32 v170, v66, v67
	v_pk_mul_f32 v[162:163], v[64:65], v[174:175] op_sel_hi:[1,0]
	v_pk_mul_f32 v[56:57], v[64:65], v[56:57]
	v_exp_f32_e32 v162, v162
	v_exp_f32_e32 v163, v163
	v_pk_fma_f32 v[160:161], v[160:161], v[176:177], v[176:177] op_sel_hi:[1,0,0]
	v_rcp_f32_e32 v160, v160
	v_rcp_f32_e32 v161, v161
	v_pk_mul_f32 v[68:69], v[68:69], v[166:167]
	v_cvt_pk_bf16_f32 v171, v68, v69
	global_store_dwordx4 v172, v[168:171], s[28:29]
	s_add_u32 s28, s28, 0xdc000
	s_addc_u32 s29, s29, 0
	v_pk_mul_f32 v[164:165], v[58:59], v[174:175] op_sel_hi:[1,0]
	v_pk_mul_f32 v[50:51], v[58:59], v[50:51]
	v_exp_f32_e32 v164, v164
	v_exp_f32_e32 v165, v165
	v_mul_f32_e32 v190, 0xbfb8aa3b, v185
	v_mul_f32_e32 v192, v185, v185
	v_rcp_f32_e32 v192, v192
	v_pk_fma_f32 v[162:163], v[162:163], v[176:177], v[176:177] op_sel_hi:[1,0,0]
	v_rcp_f32_e32 v162, v162
	v_rcp_f32_e32 v163, v163
	v_pk_mul_f32 v[54:55], v[54:55], v[160:161]
	v_cvt_pk_bf16_f32 v168, v54, v55
	v_pk_mul_f32 v[166:167], v[60:61], v[174:175] op_sel_hi:[1,0]
	v_pk_mul_f32 v[52:53], v[60:61], v[52:53]
	v_exp_f32_e32 v166, v166
	v_exp_f32_e32 v167, v167
	v_pk_fma_f32 v[164:165], v[164:165], v[176:177], v[176:177] op_sel_hi:[1,0,0]
	v_rcp_f32_e32 v164, v164
	v_rcp_f32_e32 v165, v165
	v_pk_mul_f32 v[56:57], v[56:57], v[162:163]
	v_cvt_pk_bf16_f32 v169, v56, v57
	v_pk_mul_f32 v[160:161], v[46:47], v[190:191] op_sel_hi:[1,0]
	v_pk_mul_f32 v[38:39], v[46:47], v[38:39]
	v_exp_f32_e32 v160, v160
	v_exp_f32_e32 v161, v161
	v_pk_fma_f32 v[166:167], v[166:167], v[176:177], v[176:177] op_sel_hi:[1,0,0]
	v_rcp_f32_e32 v166, v166
	v_rcp_f32_e32 v167, v167
	v_pk_mul_f32 v[50:51], v[50:51], v[164:165]
	v_cvt_pk_bf16_f32 v170, v50, v51
	v_pk_mul_f32 v[162:163], v[48:49], v[190:191] op_sel_hi:[1,0]
	v_pk_mul_f32 v[40:41], v[48:49], v[40:41]
	v_exp_f32_e32 v162, v162
	v_exp_f32_e32 v163, v163
	v_pk_fma_f32 v[160:161], v[160:161], v[192:193], v[192:193] op_sel_hi:[1,0,0]
	v_rcp_f32_e32 v160, v160
	v_rcp_f32_e32 v161, v161
	v_pk_mul_f32 v[52:53], v[52:53], v[166:167]
	v_cvt_pk_bf16_f32 v171, v52, v53
	global_store_dwordx4 v172, v[168:171], s[28:29]
	s_add_u32 s28, s28, 0x2c000
	s_addc_u32 s29, s29, 0
	v_pk_mul_f32 v[164:165], v[42:43], v[190:191] op_sel_hi:[1,0]
	v_pk_mul_f32 v[34:35], v[42:43], v[34:35]
	v_exp_f32_e32 v164, v164
	v_exp_f32_e32 v165, v165
	v_mul_f32_e32 v174, 0xbfb8aa3b, v186
	v_mul_f32_e32 v176, v186, v186
	v_rcp_f32_e32 v176, v176
	v_pk_fma_f32 v[162:163], v[162:163], v[192:193], v[192:193] op_sel_hi:[1,0,0]
	v_rcp_f32_e32 v162, v162
; __device__ __forceinline__ unsigned pk2(float lo, float hi) { f32x2 v = {lo, hi}; bf16x2_t b = __builtin_convertvector(v, bf16x2_t); return __builtin_bit_cast(unsigned, b); }
; __device__ __forceinline__ float sigmoidf_(float x) { return frcp(1.0f + fexp(-x)); }
;     __device__ __forceinline__ void operator()(const Acc& acc, const Unit& u, int wr, int wc, int fr, int fq) const {
;         const int row0 = u.pm * BM + wr * 64 + fr; const int col0 = u.pn * HALF + wc * 32 + 8 * fq;
;         float rsv[2][4];
; #pragma unroll
;         for (int ai = 0; ai < 2; ++ai)
; #pragma unroll
;             for (int m = 0; m < 4; ++m) rsv[ai][m] = RTAB[u.sub * BM + ai * HALF + wr * 64 + m * 16 + fr];
; #pragma unroll
;         for (int ai = 0; ai < 2; ++ai)
; #pragma unroll
;             for (int m = 0; m < 4; ++m) { const int row = row0 + ai * HALF + m * 16; const float rs = rsv[ai][m];
;                 float o[8];
; #pragma unroll
;                 for (int n = 0; n < 2; ++n)
; #pragma unroll
;                     for (int e = 0; e < 4; ++e) { const float g = acc[ai][0][m][n][e] * rs, up = acc[ai][1][m][n][e] * rs; o[4 * n + e] = g * sigmoidf_(g) * up; }
;                 u32x4 w; w.x = pk2(o[0], o[1]); w.y = pk2(o[2], o[3]); w.z = pk2(o[4], o[5]); w.w = pk2(o[6], o[7]);
;                 *(u32x4*)(ACT + (size_t)row * DFF + col0) = w; }
;     }
	v_rcp_f32_e32 v163, v163
	v_pk_mul_f32 v[38:39], v[38:39], v[160:161]
	v_cvt_pk_bf16_f32 v168, v38, v39
	v_pk_mul_f32 v[166:167], v[44:45], v[190:191] op_sel_hi:[1,0]
	v_pk_mul_f32 v[36:37], v[44:45], v[36:37]
	v_exp_f32_e32 v166, v166
	v_exp_f32_e32 v167, v167
	v_pk_fma_f32 v[164:165], v[164:165], v[192:193], v[192:193] op_sel_hi:[1,0,0]
	v_rcp_f32_e32 v164, v164
	v_rcp_f32_e32 v165, v165
	v_pk_mul_f32 v[40:41], v[40:41], v[162:163]
	v_cvt_pk_bf16_f32 v169, v40, v41
	v_pk_mul_f32 v[160:161], v[30:31], v[174:175] op_sel_hi:[1,0]
	v_pk_mul_f32 v[22:23], v[30:31], v[22:23]
	v_exp_f32_e32 v160, v160
	v_exp_f32_e32 v161, v161
	v_pk_fma_f32 v[166:167], v[166:167], v[192:193], v[192:193] op_sel_hi:[1,0,0]
	v_rcp_f32_e32 v166, v166
	v_rcp_f32_e32 v167, v167
	v_pk_mul_f32 v[34:35], v[34:35], v[164:165]
	v_cvt_pk_bf16_f32 v170, v34, v35
	v_pk_mul_f32 v[162:163], v[32:33], v[174:175] op_sel_hi:[1,0]
	v_pk_mul_f32 v[24:25], v[32:33], v[24:25]
	v_exp_f32_e32 v162, v162
	v_exp_f32_e32 v163, v163
	v_pk_fma_f32 v[160:161], v[160:161], v[176:177], v[176:177] op_sel_hi:[1,0,0]
	v_rcp_f32_e32 v160, v160
	v_rcp_f32_e32 v161, v161
	v_pk_mul_f32 v[36:37], v[36:37], v[166:167]
	v_cvt_pk_bf16_f32 v171, v36, v37
	global_store_dwordx4 v172, v[168:171], s[28:29]
	s_add_u32 s28, s28, 0x2c000
	s_addc_u32 s29, s29, 0
	v_pk_mul_f32 v[164:165], v[26:27], v[174:175] op_sel_hi:[1,0]
	v_pk_mul_f32 v[18:19], v[26:27], v[18:19]
	v_exp_f32_e32 v164, v164
	v_exp_f32_e32 v165, v165
	v_mul_f32_e32 v190, 0xbfb8aa3b, v187
	v_mul_f32_e32 v192, v187, v187
	v_rcp_f32_e32 v192, v192
	v_pk_fma_f32 v[162:163], v[162:163], v[176:177], v[176:177] op_sel_hi:[1,0,0]
	v_rcp_f32_e32 v162, v162
	v_rcp_f32_e32 v163, v163
	v_pk_mul_f32 v[22:23], v[22:23], v[160:161]
	v_cvt_pk_bf16_f32 v168, v22, v23
	v_pk_mul_f32 v[166:167], v[28:29], v[174:175] op_sel_hi:[1,0]
	v_pk_mul_f32 v[20:21], v[28:29], v[20:21]
	v_exp_f32_e32 v166, v166
	v_exp_f32_e32 v167, v167
	v_pk_fma_f32 v[164:165], v[164:165], v[176:177], v[176:177] op_sel_hi:[1,0,0]
	v_rcp_f32_e32 v164, v164
	v_rcp_f32_e32 v165, v165
	v_pk_mul_f32 v[24:25], v[24:25], v[162:163]
	v_cvt_pk_bf16_f32 v169, v24, v25
	v_pk_mul_f32 v[160:161], v[14:15], v[190:191] op_sel_hi:[1,0]
	v_pk_mul_f32 v[6:7], v[14:15], v[6:7]
	v_exp_f32_e32 v160, v160
	v_exp_f32_e32 v161, v161
	v_pk_fma_f32 v[166:167], v[166:167], v[176:177], v[176:177] op_sel_hi:[1,0,0]
	v_rcp_f32_e32 v166, v166
	v_rcp_f32_e32 v167, v167
	v_pk_mul_f32 v[18:19], v[18:19], v[164:165]
	v_cvt_pk_bf16_f32 v170, v18, v19
	v_pk_mul_f32 v[162:163], v[16:17], v[190:191] op_sel_hi:[1,0]
	v_pk_mul_f32 v[8:9], v[16:17], v[8:9]
	v_exp_f32_e32 v162, v162
	v_exp_f32_e32 v163, v163
	v_pk_fma_f32 v[160:161], v[160:161], v[192:193], v[192:193] op_sel_hi:[1,0,0]
	v_rcp_f32_e32 v160, v160
	v_rcp_f32_e32 v161, v161
	v_pk_mul_f32 v[20:21], v[20:21], v[166:167]
	v_cvt_pk_bf16_f32 v171, v20, v21
	global_store_dwordx4 v172, v[168:171], s[28:29]
	s_add_u32 s28, s28, 0x2c000
	s_addc_u32 s29, s29, 0
	v_pk_mul_f32 v[164:165], v[10:11], v[190:191] op_sel_hi:[1,0]
	v_pk_mul_f32 v[2:3], v[10:11], v[2:3]
	v_exp_f32_e32 v164, v164
	v_exp_f32_e32 v165, v165
	v_pk_fma_f32 v[162:163], v[162:163], v[192:193], v[192:193] op_sel_hi:[1,0,0]
	v_rcp_f32_e32 v162, v162
	v_rcp_f32_e32 v163, v163
	v_pk_mul_f32 v[6:7], v[6:7], v[160:161]
	v_cvt_pk_bf16_f32 v168, v6, v7
	v_pk_mul_f32 v[166:167], v[12:13], v[190:191] op_sel_hi:[1,0]
	v_pk_mul_f32 v[4:5], v[12:13], v[4:5]
	v_exp_f32_e32 v166, v166
	v_exp_f32_e32 v167, v167
	v_pk_fma_f32 v[164:165], v[164:165], v[192:193], v[192:193] op_sel_hi:[1,0,0]
	v_rcp_f32_e32 v164, v164
	v_rcp_f32_e32 v165, v165
	v_pk_mul_f32 v[8:9], v[8:9], v[162:163]
	v_cvt_pk_bf16_f32 v169, v8, v9
	v_pk_fma_f32 v[166:167], v[166:167], v[192:193], v[192:193] op_sel_hi:[1,0,0]
	v_rcp_f32_e32 v166, v166
	v_rcp_f32_e32 v167, v167
	v_pk_mul_f32 v[2:3], v[2:3], v[164:165]
	v_cvt_pk_bf16_f32 v170, v2, v3
	s_nop 0
	v_pk_mul_f32 v[4:5], v[4:5], v[166:167]
	v_cvt_pk_bf16_f32 v171, v4, v5
	global_store_dwordx4 v172, v[168:171], s[28:29]
	s_andn2_b64 vcc, exec, s[0:1]
	s_mov_b64 s[0:1], -1
	s_cbranch_vccnz .LBB0_1100
	s_andn2_b64 vcc, exec, s[4:5]
	s_cbranch_vccnz .LBB0_1099
	s_barrier
	s_branch .LBB0_1099
